# loop-edge edit: gate_up has-next test moved from two 64-bit VALU compares to s_cmp/s_cselect on the scalar unit
# speedup vs baseline: 1.0040x; 1.0040x over previous
.LBB0_251:
	s_add_i32 s61, s62, 1
	s_mul_i32 s2, s61, s56
	s_mul_hi_u32 s3, s61, s57
	s_add_i32 s3, s3, s2
	s_mul_i32 s2, s61, s57
	s_add_u32 s22, s2, s96
	s_addc_u32 s23, s3, s35
	s_cmp_gt_u32 s22, 0x15ff
	s_cselect_b64 vcc, exec, 0
	s_cselect_b64 s[2:3], 0, exec
	s_cbranch_scc1 .LBB0_253
	s_ashr_i32 s12, s22, 31
	s_lshr_b32 s12, s12, 29
	s_add_i32 s12, s22, s12
	s_ashr_i32 s13, s12, 3
	s_and_b32 s12, s12, -8
	s_sub_i32 s12, s22, s12
	s_cmp_lt_i32 s12, 0
	s_movk_i32 s20, 0x2c1
	s_cselect_b32 s20, s20, 0x2c0
	s_mul_i32 s12, s12, s20
	s_add_i32 s12, s12, s13
	s_mul_hi_i32 s13, s12, 0x2e8ba2e9
	s_lshr_b32 s20, s13, 31
	s_ashr_i32 s13, s13, 5
	s_add_i32 s13, s13, s20
	s_lshl_b32 s20, s13, 3
	s_mulk_i32 s13, 0xb0
	s_sub_i32 s13, s12, s13
	s_ashr_i32 s12, s13, 3
	s_and_b32 s13, s13, 7
	s_add_i32 s20, s20, s13

.LBB0_1066:
	s_add_i32 s53, s56, 1
	s_mul_i32 s2, s53, s43
	s_mul_hi_u32 s3, s53, s46
	s_add_i32 s3, s3, s2
	s_mul_i32 s2, s53, s46
	s_add_u32 s18, s2, s96
	s_addc_u32 s19, s3, s34
	s_cmp_gt_u32 s18, 0x15ff
	s_cselect_b64 vcc, exec, 0
	s_cselect_b64 s[2:3], 0, exec
	s_cbranch_scc1 .LBB0_1068
	s_ashr_i32 s14, s18, 31
	s_lshr_b32 s14, s14, 29
	s_add_i32 s14, s18, s14
	s_ashr_i32 s15, s14, 3
	s_and_b32 s14, s14, -8
	s_sub_i32 s14, s18, s14
	s_cmp_lt_i32 s14, 0
	s_cselect_b32 s16, s47, 0x2c0
	s_mul_i32 s14, s14, s16
	s_add_i32 s14, s14, s15
	s_mul_hi_i32 s15, s14, 0x2e8ba2e9
	s_lshr_b32 s16, s15, 31
	s_ashr_i32 s15, s15, 5
	s_add_i32 s15, s15, s16
	s_lshl_b32 s16, s15, 3
	s_mulk_i32 s15, 0xb0
	s_sub_i32 s15, s14, s15
	s_ashr_i32 s14, s15, 3
	s_and_b32 s15, s15, 7
	s_add_i32 s16, s16, s15

.LBB0_1358:
	s_add_i32 s55, s56, 1
	s_mul_i32 s2, s55, s47
	s_mul_hi_u32 s3, s55, s48
	s_add_i32 s3, s3, s2
	s_mul_i32 s2, s55, s48
	s_add_u32 s18, s2, s96
	s_addc_u32 s19, s3, s34
	s_cmp_gt_u32 s18, 0x15ff
	s_cselect_b64 vcc, exec, 0
	s_cselect_b64 s[2:3], 0, exec
	s_cbranch_scc1 .LBB0_1360
	s_ashr_i32 s6, s18, 31
	s_lshr_b32 s6, s6, 29
	s_add_i32 s6, s18, s6
	s_ashr_i32 s7, s6, 3
	s_and_b32 s6, s6, -8
	s_sub_i32 s6, s18, s6
	s_cmp_lt_i32 s6, 0
	s_cselect_b32 s16, s49, 0x2c0
	s_mul_i32 s6, s6, s16
	s_add_i32 s6, s6, s7
	s_mul_hi_i32 s7, s6, 0x2e8ba2e9
	s_lshr_b32 s16, s7, 31
	s_ashr_i32 s7, s7, 5
	s_add_i32 s7, s7, s16
	s_lshl_b32 s16, s7, 3
	s_mulk_i32 s7, 0xb0
	s_sub_i32 s7, s6, s7
	s_ashr_i32 s6, s7, 3
	s_and_b32 s7, s7, 7
	s_add_i32 s16, s16, s7

.LBB0_1934:
	s_add_i32 s49, s52, 1
	s_mul_i32 s2, s49, s41
	s_mul_hi_u32 s3, s49, s42
	s_add_i32 s3, s3, s2
	s_mul_i32 s2, s49, s42
	s_add_u32 s14, s2, s96
	s_addc_u32 s15, s3, s28
	s_cmp_gt_u32 s14, 0x15ff
	s_cselect_b64 vcc, exec, 0
	s_cselect_b64 s[2:3], 0, exec
	s_cbranch_scc1 .LBB0_1936
	s_ashr_i32 s10, s14, 31
	s_lshr_b32 s10, s10, 29
	s_add_i32 s10, s14, s10
	s_ashr_i32 s11, s10, 3
	s_and_b32 s10, s10, -8
	s_sub_i32 s10, s14, s10
	s_cmp_lt_i32 s10, 0
	s_cselect_b32 s12, s43, 0x2c0
	s_mul_i32 s10, s10, s12
	s_add_i32 s10, s10, s11
	s_mul_hi_i32 s11, s10, 0x2e8ba2e9
	s_lshr_b32 s12, s11, 31
	s_ashr_i32 s11, s11, 5
	s_add_i32 s11, s11, s12
	s_lshl_b32 s12, s11, 3
	s_mulk_i32 s11, 0xb0
	s_sub_i32 s11, s10, s11
	s_ashr_i32 s10, s11, 3
	s_and_b32 s11, s11, 7
	s_add_i32 s12, s12, s11
